# row pass, even groups: BIAS1 weight loads issued after the modulation-vector loads instead of before the adaLN poll; first-row waits duplicated per path
# baseline (speedup 1.0000x reference)
.LBB0_118:
	s_cmp_lt_i32 s20, 2
	s_cselect_b64 s[4:5], -1, 0
	s_cmp_gt_i32 s21, 1
	s_waitcnt lgkmcnt(0)
	s_cselect_b64 s[6:7], -1, 0
	s_and_b64 s[4:5], s[4:5], s[6:7]
	s_andn2_b64 vcc, exec, s[4:5]
	s_mov_b64 s[4:5], 0
	s_cbranch_vccnz .LBB0_302
	s_ashr_i32 s4, s2, 31
	s_lshr_b32 s4, s4, 29
	s_add_i32 s4, s2, s4
	s_and_b32 s5, s4, 0x1ffffff8
	s_lshr_b32 s3, s33, 3
	s_sub_i32 s5, s2, s5
	s_mul_i32 s3, s3, s5
	s_lshr_b32 s4, s4, 3
	s_add_i32 s3, s3, s4
	s_bitcmp0_b32 s2, 0
	s_cselect_b64 s[4:5], -1, 0
	s_lshl_b32 s6, s2, 4
	s_and_b32 s6, s6, 0x60
	s_ashr_i32 s7, s2, 3
	s_add_i32 s6, s6, s7
	s_mul_i32 s6, s6, 28
	s_ashr_i32 s7, s6, 31
	s_and_b64 s[10:11], s[84:85], exec
	s_cselect_b32 s3, s3, s2
	s_lshl_b32 s3, s3, 3
	s_add_i32 s3, s3, s75
	s_lshl_b32 s42, s3, 3
	s_mov_b64 s[8:9], s[0:1]
	s_or_b32 s30, s42, 3
	v_mov_b32_e32 v144, v244
	s_cmpk_gt_i32 s3, 0x7ff
	s_load_dwordx2 s[38:39], s[8:9], 0x0
	s_load_dwordx2 s[40:41], s[8:9], 0x10
	s_load_dwordx2 s[50:51], s[8:9], 0x20
	s_load_dwordx2 s[10:11], s[8:9], 0x70
	s_cselect_b64 s[54:55], -1, 0
	s_add_i32 s65, s42, 0xffffc000
	s_ashr_i32 s43, s42, 31
	s_cmpk_lt_i32 s3, 0x800
	s_cselect_b32 s13, s43, 0
	s_cselect_b32 s12, s42, s65
	s_waitcnt lgkmcnt(0)
	s_cselect_b32 s14, s39, s41
	s_cselect_b32 s15, s38, s40
	s_lshl_b64 s[12:13], s[12:13], 12
	s_add_u32 s12, s15, s12
	s_addc_u32 s13, s14, s13
	s_cmpk_gt_i32 s30, 0x3fff
	v_ashrrev_i32_e32 v145, 31, v144
	s_cselect_b64 s[36:37], -1, 0
	s_add_i32 s64, s42, 0xffffc003
	s_ashr_i32 s31, s30, 31
	v_lshlrev_b64 v[146:147], 4, v[144:145]
	s_cmpk_lt_i32 s30, 0x4000
	v_lshl_add_u64 v[0:1], s[12:13], 0, v[146:147]
	s_cselect_b32 s13, s31, 0
	s_cselect_b32 s12, s30, s64
	s_cselect_b32 s14, s39, s41
	s_cselect_b32 s15, s38, s40
	s_lshl_b64 s[12:13], s[12:13], 12
	s_add_u32 s12, s15, s12
	s_addc_u32 s13, s14, s13
	s_or_b32 s48, s42, 1
	s_cmpk_gt_i32 s48, 0x3fff
	global_load_dwordx4 v[108:111], v[0:1], off nt
	global_load_dwordx4 v[104:107], v[0:1], off offset:1024 nt
	global_load_dwordx4 v[100:103], v[0:1], off offset:2048 nt
	global_load_dwordx4 v[96:99], v[0:1], off offset:3072 nt
	v_lshl_add_u64 v[0:1], s[12:13], 0, v[146:147]
	s_cselect_b64 s[52:53], -1, 0
	s_add_i32 s12, s42, 0xffffc001
	s_ashr_i32 s49, s48, 31
	s_cmpk_lt_i32 s48, 0x4000
	s_cselect_b32 s13, s49, 0
	s_cselect_b32 s12, s48, s12
	s_cselect_b32 s14, s39, s41
	s_cselect_b32 s15, s38, s40
	s_lshl_b64 s[12:13], s[12:13], 12
	s_add_u32 s12, s15, s12
	s_addc_u32 s13, s14, s13
	s_or_b32 s16, s42, 4
	s_cmpk_gt_i32 s16, 0x3fff
	s_cselect_b64 s[18:19], -1, 0
	s_add_i32 s29, s42, 0xffffc004
	s_ashr_i32 s17, s16, 31
	s_cmpk_lt_i32 s16, 0x4000
	global_load_dwordx4 v[44:47], v[0:1], off nt
	global_load_dwordx4 v[40:43], v[0:1], off offset:1024 nt
	global_load_dwordx4 v[36:39], v[0:1], off offset:2048 nt
	global_load_dwordx4 v[32:35], v[0:1], off offset:3072 nt
	v_lshl_add_u64 v[0:1], s[12:13], 0, v[146:147]
	s_cselect_b32 s13, s17, 0
	s_cselect_b32 s12, s16, s29
	s_cselect_b32 s14, s39, s41
	s_cselect_b32 s15, s38, s40
	s_lshl_b64 s[12:13], s[12:13], 12
	s_add_u32 s12, s15, s12
	s_addc_u32 s13, s14, s13
	s_or_b32 s44, s42, 2
	s_cmpk_gt_i32 s44, 0x3fff
	global_load_dwordx4 v[92:95], v[0:1], off nt
	global_load_dwordx4 v[88:91], v[0:1], off offset:1024 nt
	global_load_dwordx4 v[84:87], v[0:1], off offset:2048 nt
	global_load_dwordx4 v[76:79], v[0:1], off offset:3072 nt
	v_lshl_add_u64 v[0:1], s[12:13], 0, v[146:147]
	s_cselect_b64 s[46:47], -1, 0
	s_add_i32 s12, s42, 0xffffc002
	s_ashr_i32 s45, s44, 31
	s_cmpk_lt_i32 s44, 0x4000
	s_cselect_b32 s13, s45, 0
	s_cselect_b32 s12, s44, s12
	s_cselect_b32 s14, s39, s41
	s_cselect_b32 s15, s38, s40
	s_lshl_b64 s[12:13], s[12:13], 12
	s_add_u32 s12, s15, s12
	s_addc_u32 s13, s14, s13
	global_load_dwordx4 v[28:31], v[0:1], off nt
	global_load_dwordx4 v[24:27], v[0:1], off offset:1024 nt
	global_load_dwordx4 v[16:19], v[0:1], off offset:2048 nt
	global_load_dwordx4 v[12:15], v[0:1], off offset:3072 nt
	v_lshl_add_u64 v[0:1], s[12:13], 0, v[146:147]
	s_or_b32 s12, s42, 5
	s_cmpk_gt_i32 s12, 0x3fff
	s_cselect_b64 s[14:15], -1, 0
	s_add_i32 s28, s42, 0xffffc005
	s_ashr_i32 s13, s12, 31
	s_cmpk_lt_i32 s12, 0x4000
	s_cselect_b32 s27, s13, 0
	s_cselect_b32 s26, s12, s28
	s_cselect_b32 s34, s39, s41
	s_cselect_b32 s35, s38, s40
	s_lshl_b64 s[26:27], s[26:27], 12
	s_add_u32 s26, s35, s26
	s_addc_u32 s27, s34, s27
	global_load_dwordx4 v[68:71], v[0:1], off nt
	global_load_dwordx4 v[60:63], v[0:1], off offset:1024 nt
	global_load_dwordx4 v[52:55], v[0:1], off offset:2048 nt
	global_load_dwordx4 v[48:51], v[0:1], off offset:3072 nt
	v_lshl_add_u64 v[0:1], s[26:27], 0, v[146:147]
	global_load_dwordx4 v[20:23], v[0:1], off nt
	global_load_dwordx4 v[8:11], v[0:1], off offset:1024 nt
	global_load_dwordx4 v[4:7], v[0:1], off offset:2048 nt
	s_nop 0
	global_load_dwordx4 v[0:3], v[0:1], off offset:3072 nt
	s_load_dwordx2 s[8:9], s[8:9], 0xa8
	v_and_b32_e32 v217, 15, v144
	v_add_u32_e32 v152, s76, v144
	v_cmp_gt_u32_e32 vcc, 14, v217
	v_ashrrev_i32_e32 v218, 4, v152
	s_and_b64 s[34:35], s[4:5], vcc
	v_mov_b32_e32 v186, 0
	v_mov_b32_e32 v189, 0
	v_mov_b32_e32 v190, 0
	v_mov_b32_e32 v191, 0
	v_mov_b32_e32 v188, 0
	v_mov_b32_e32 v192, 0
	v_mov_b32_e32 v185, 0
	v_mov_b32_e32 v187, 0
	v_mov_b32_e32 v194, 0
	v_mov_b32_e32 v197, 0
	v_mov_b32_e32 v198, 0
	v_mov_b32_e32 v199, 0
	v_mov_b32_e32 v196, 0
	v_mov_b32_e32 v200, 0
	v_mov_b32_e32 v193, 0
	v_mov_b32_e32 v195, 0
	v_mov_b32_e32 v202, 0
	v_mov_b32_e32 v205, 0
	v_mov_b32_e32 v206, 0
	v_mov_b32_e32 v207, 0
	v_mov_b32_e32 v204, 0
	v_mov_b32_e32 v208, 0
	v_mov_b32_e32 v201, 0
	v_mov_b32_e32 v203, 0
	v_mov_b32_e32 v209, 0
	v_mov_b32_e32 v211, 0
	v_mov_b32_e32 v212, 0
	v_mov_b32_e32 v213, 0
	v_mov_b32_e32 v210, 0
	v_mov_b32_e32 v216, 0
	v_mov_b32_e32 v214, 0
	v_mov_b32_e32 v215, 0
	s_mov_b64 s[82:83], s[34:35]
	s_mov_b32 s80, s6
	s_mov_b64 s[86:87], s[10:11]
	v_mov_b32_e32 v153, 0
	v_mov_b32_e32 v157, 0
	v_mov_b32_e32 v158, 0
	v_mov_b32_e32 v159, 0
	v_mov_b32_e32 v156, 0
	v_mov_b32_e32 v160, 0
	v_mov_b32_e32 v154, 0
	v_mov_b32_e32 v155, 0
	v_mov_b32_e32 v162, 0
	v_mov_b32_e32 v165, 0
	v_mov_b32_e32 v166, 0
	v_mov_b32_e32 v167, 0
	v_mov_b32_e32 v164, 0
	v_mov_b32_e32 v168, 0
	v_mov_b32_e32 v161, 0
	v_mov_b32_e32 v163, 0
	v_mov_b32_e32 v170, 0
	v_mov_b32_e32 v173, 0
	v_mov_b32_e32 v174, 0
	v_mov_b32_e32 v175, 0
	v_mov_b32_e32 v172, 0
	v_mov_b32_e32 v176, 0
	v_mov_b32_e32 v169, 0
	v_mov_b32_e32 v171, 0
	v_mov_b32_e32 v177, 0
	v_mov_b32_e32 v179, 0
	v_mov_b32_e32 v180, 0
	v_mov_b32_e32 v181, 0
	v_mov_b32_e32 v178, 0
	v_mov_b32_e32 v184, 0
	v_mov_b32_e32 v182, 0
	v_mov_b32_e32 v183, 0
	s_cmp_lt_u32 s74, 64
	s_cselect_b64 s[10:11], -1, 0
	s_cmp_gt_u32 s74, 63
	s_cbranch_scc1 .LBB0_160
	v_mov_b32_e32 v56, 0x28000
	s_waitcnt lgkmcnt(0)
	buffer_inv sc1
	global_load_dword v56, v56, s[8:9] sc1
	s_movk_i32 s26, 0xbf
	s_add_u32 s34, s8, 0x28000
	s_addc_u32 s35, s9, 0
	s_waitcnt vmcnt(0)
	v_cmp_lt_u32_e32 vcc, s26, v56
	s_cbranch_vccnz .LBB0_159
	s_mov_b32 s27, 0x3ffff8
	v_mov_b32_e32 v56, 0
	s_movk_i32 s58, 0xc0
	s_branch .LBB0_151

.LBB0_160:
	s_waitcnt lgkmcnt(0)
	s_add_u32 s34, s8, 0x100000
	s_addc_u32 s35, s9, 0
	s_add_u32 s58, s8, 0x1800000
	s_addc_u32 s59, s9, 0
	s_ashr_i32 s56, s3, 8
	s_mul_i32 s26, s56, 0xc00
	s_ashr_i32 s27, s26, 31
	s_lshl_b64 s[26:27], s[26:27], 2
	v_lshlrev_b32_e32 v150, 2, v144
	s_add_u32 s26, s34, s26
	v_ashrrev_i32_e32 v151, 31, v150
	s_addc_u32 s27, s35, s27
	v_lshlrev_b64 v[56:57], 2, v[150:151]
	v_lshl_add_u64 v[148:149], s[50:51], 0, v[56:57]
	v_lshl_add_u64 v[56:57], s[26:27], 0, v[56:57]
	s_mov_b64 s[26:27], 0x1000
	v_lshl_add_u64 v[58:59], v[56:57], 0, s[26:27]
	s_movk_i32 s26, 0x1000
	v_add_co_u32_e32 v64, vcc, s26, v56
	s_waitcnt vmcnt(63) expcnt(7) lgkmcnt(15)
	s_nop 0
	v_addc_co_u32_e32 v65, vcc, 0, v57, vcc
	s_barrier
	global_load_dwordx4 v[132:135], v[148:149], off
	global_load_dwordx4 v[124:127], v[148:149], off offset:1024
	global_load_dwordx4 v[80:83], v[56:57], off
	global_load_dwordx4 v[72:75], v[56:57], off offset:1024
	global_load_dwordx4 v[136:139], v[58:59], off offset:1024
	global_load_dwordx4 v[128:131], v[58:59], off offset:2048
	global_load_dwordx4 v[120:123], v[148:149], off offset:2048
	global_load_dwordx4 v[112:115], v[148:149], off offset:3072
	global_load_dwordx4 v[140:143], v[64:65], off
	global_load_dwordx4 v[116:119], v[58:59], off offset:3072
	s_nop 0
	global_load_dwordx4 v[64:67], v[56:57], off offset:2048
	s_nop 0
	global_load_dwordx4 v[56:59], v[56:57], off offset:3072
	s_and_saveexec_b64 s[66:67], s[82:83]
	s_cbranch_execz .LBB0_133
	v_add_u32_e32 v228, s80, v217
	v_and_b32_e32 v230, 0xffffffe0, v228
	s_movk_i32 s78, 0x3ff
	v_cmp_lt_i32_e32 vcc, s78, v230
	s_and_saveexec_b64 s[78:79], vcc
	s_xor_b64 s[68:69], exec, s[78:79]
	s_cbranch_execz .LBB0_130
	s_movk_i32 s78, 0x7ff
	v_cmp_lt_u32_e32 vcc, s78, v228
	s_and_saveexec_b64 s[78:79], vcc
	s_xor_b64 s[70:71], exec, s[78:79]
	s_cbranch_execz .LBB0_127
	s_movk_i32 s78, 0xbff
	v_cmp_lt_u32_e32 vcc, s78, v228
	s_and_saveexec_b64 s[78:79], vcc
	s_xor_b64 s[72:73], exec, s[78:79]
	v_add_u32_e32 v229, 0xfffff600, v230
	s_andn2_saveexec_b64 s[72:73], s[72:73]
	s_cbranch_execz .LBB0_126
	v_add_u32_e32 v229, 0xfffff800, v228
	v_and_b32_e32 v230, 0x80, v228
	v_mov_b32_e32 v231, 0xa00
	v_mov_b32_e32 v232, 0x800
	v_cmp_eq_u32_e32 vcc, 0, v230
	v_lshrrev_b32_e32 v229, 1, v229
	v_and_b32_e32 v229, 0x7fffff80, v229
	v_cndmask_b32_e32 v230, v231, v232, vcc
	v_add_u32_e32 v229, v230, v229
	s_movk_i32 s78, 0x60
	v_and_or_b32 v229, v228, s78, v229
.LBB0_126:
	s_or_b64 exec, exec, s[72:73]
.LBB0_127:
	s_andn2_saveexec_b64 s[70:71], s[70:71]
	s_cbranch_execz .LBB0_129
	v_add_u32_e32 v229, 0xfffffc00, v228
	v_and_b32_e32 v230, 0x80, v228
	v_mov_b32_e32 v231, 0xc00
	v_mov_b32_e32 v232, 0x600
	v_cmp_eq_u32_e32 vcc, 0, v230
	v_lshrrev_b32_e32 v229, 1, v229
	v_and_b32_e32 v229, 0x7fffff80, v229
	v_cndmask_b32_e32 v230, v231, v232, vcc
	v_add_u32_e32 v229, v230, v229
	s_movk_i32 s78, 0x60
	v_and_or_b32 v229, v228, s78, v229

.LBB0_130:
	s_andn2_saveexec_b64 s[68:69], s[68:69]
	v_lshlrev_b32_e32 v229, 3, v228
	v_ashrrev_i32_e32 v230, 1, v228
	v_and_b32_e32 v229, 0x400, v229
	v_and_b32_e32 v230, 0xffffff80, v230
	v_add_u32_e32 v229, v229, v230
	s_movk_i32 s78, 0x60
	v_and_or_b32 v229, v228, s78, v229
	s_or_b64 exec, exec, s[68:69]
	v_and_b32_e32 v228, 31, v228
	v_add_u32_e32 v228, v229, v228
	v_ashrrev_i32_e32 v229, 31, v228
	v_lshlrev_b32_e32 v245, 5, v218
	v_lshl_add_u64 v[228:229], v[228:229], 2, s[86:87]
	s_movk_i32 s68, 0x3800
	v_mad_i64_i32 v[230:231], s[78:79], v245, s68, v[228:229]
	v_or_b32_e32 v232, 1, v245
	v_or_b32_e32 v234, 2, v245
	v_or_b32_e32 v236, 3, v245
	v_or_b32_e32 v238, 4, v245
	v_or_b32_e32 v240, 5, v245
	v_or_b32_e32 v242, 6, v245
	v_or_b32_e32 v246, 7, v245
	v_mad_i64_i32 v[232:233], s[78:79], v232, s68, v[228:229]
	v_mad_i64_i32 v[234:235], s[78:79], v234, s68, v[228:229]
	v_mad_i64_i32 v[236:237], s[78:79], v236, s68, v[228:229]
	v_mad_i64_i32 v[238:239], s[78:79], v238, s68, v[228:229]
	v_mad_i64_i32 v[240:241], s[78:79], v240, s68, v[228:229]
	v_mad_i64_i32 v[242:243], s[78:79], v242, s68, v[228:229]
	v_mad_i64_i32 v[246:247], s[78:79], v246, s68, v[228:229]
	global_load_dword v186, v[230:231], off nt
	global_load_dword v189, v[232:233], off nt
	global_load_dword v190, v[234:235], off nt
	global_load_dword v191, v[236:237], off nt
	global_load_dword v188, v[238:239], off nt
	global_load_dword v192, v[240:241], off nt
	global_load_dword v185, v[242:243], off nt
	global_load_dword v187, v[246:247], off nt
	v_or_b32_e32 v230, 8, v245
	v_mad_i64_i32 v[230:231], s[78:79], v230, s68, v[228:229]
	v_or_b32_e32 v232, 9, v245
	v_or_b32_e32 v234, 10, v245
	v_or_b32_e32 v236, 11, v245
	v_or_b32_e32 v238, 12, v245
	v_or_b32_e32 v240, 13, v245
	v_or_b32_e32 v242, 14, v245
	v_or_b32_e32 v246, 15, v245
	v_mad_i64_i32 v[232:233], s[78:79], v232, s68, v[228:229]
	v_mad_i64_i32 v[234:235], s[78:79], v234, s68, v[228:229]
	v_mad_i64_i32 v[236:237], s[78:79], v236, s68, v[228:229]
	v_mad_i64_i32 v[238:239], s[78:79], v238, s68, v[228:229]
	v_mad_i64_i32 v[240:241], s[78:79], v240, s68, v[228:229]
	v_mad_i64_i32 v[242:243], s[78:79], v242, s68, v[228:229]
	v_mad_i64_i32 v[246:247], s[78:79], v246, s68, v[228:229]
	global_load_dword v194, v[230:231], off nt
	global_load_dword v197, v[232:233], off nt
	global_load_dword v198, v[234:235], off nt
	global_load_dword v199, v[236:237], off nt
	global_load_dword v196, v[238:239], off nt
	global_load_dword v200, v[240:241], off nt
	global_load_dword v193, v[242:243], off nt
	global_load_dword v195, v[246:247], off nt
	v_or_b32_e32 v230, 16, v245
	v_mad_i64_i32 v[230:231], s[78:79], v230, s68, v[228:229]
	v_or_b32_e32 v232, 17, v245
	v_or_b32_e32 v234, 18, v245
	v_or_b32_e32 v236, 19, v245
	v_or_b32_e32 v238, 20, v245
	v_or_b32_e32 v240, 21, v245
	v_or_b32_e32 v242, 22, v245
	v_or_b32_e32 v246, 23, v245
	v_mad_i64_i32 v[232:233], s[78:79], v232, s68, v[228:229]
	v_mad_i64_i32 v[234:235], s[78:79], v234, s68, v[228:229]
	v_mad_i64_i32 v[236:237], s[78:79], v236, s68, v[228:229]
	v_mad_i64_i32 v[238:239], s[78:79], v238, s68, v[228:229]
	v_mad_i64_i32 v[240:241], s[78:79], v240, s68, v[228:229]
	v_mad_i64_i32 v[242:243], s[78:79], v242, s68, v[228:229]
	v_mad_i64_i32 v[246:247], s[78:79], v246, s68, v[228:229]
	global_load_dword v202, v[230:231], off nt
	global_load_dword v205, v[232:233], off nt
	global_load_dword v206, v[234:235], off nt
	global_load_dword v207, v[236:237], off nt
	global_load_dword v204, v[238:239], off nt
	global_load_dword v208, v[240:241], off nt
	global_load_dword v201, v[242:243], off nt
	global_load_dword v203, v[246:247], off nt
	v_or_b32_e32 v230, 24, v245
	v_mad_i64_i32 v[230:231], s[78:79], v230, s68, v[228:229]
	v_or_b32_e32 v232, 25, v245
	v_or_b32_e32 v234, 26, v245
	v_or_b32_e32 v236, 27, v245
	v_or_b32_e32 v238, 28, v245
	v_or_b32_e32 v240, 29, v245
	v_or_b32_e32 v242, 30, v245
	v_or_b32_e32 v246, 31, v245
	v_mad_i64_i32 v[232:233], s[78:79], v232, s68, v[228:229]
	v_mad_i64_i32 v[234:235], s[78:79], v234, s68, v[228:229]
	v_mad_i64_i32 v[236:237], s[78:79], v236, s68, v[228:229]
	v_mad_i64_i32 v[238:239], s[78:79], v238, s68, v[228:229]
	v_mad_i64_i32 v[240:241], s[78:79], v240, s68, v[228:229]
	v_mad_i64_i32 v[242:243], s[78:79], v242, s68, v[228:229]
	v_mad_i64_i32 v[228:229], s[78:79], v246, s68, v[228:229]
	global_load_dword v209, v[230:231], off nt
	global_load_dword v211, v[232:233], off nt
	global_load_dword v212, v[234:235], off nt
	global_load_dword v213, v[236:237], off nt
	global_load_dword v210, v[238:239], off nt
	global_load_dword v216, v[240:241], off nt
	global_load_dword v214, v[242:243], off nt
	global_load_dword v215, v[228:229], off nt
.LBB0_133:
	s_or_b64 exec, exec, s[66:67]
	s_and_saveexec_b64 s[66:67], s[82:83]
	s_cbranch_execz .LBB0_147
	v_add3_u32 v228, s80, 14, v217
	v_and_b32_e32 v230, 0xffffffe0, v228
	s_movk_i32 s78, 0x3ff
	v_cmp_lt_i32_e32 vcc, s78, v230
	s_and_saveexec_b64 s[78:79], vcc
	s_xor_b64 s[82:83], exec, s[78:79]
	s_cbranch_execz .LBB0_144
	s_movk_i32 s78, 0x7ff
	v_cmp_lt_u32_e32 vcc, s78, v228
	s_and_saveexec_b64 s[78:79], vcc
	s_xor_b64 s[68:69], exec, s[78:79]
	s_cbranch_execz .LBB0_141
	s_movk_i32 s78, 0xbff
	v_cmp_lt_u32_e32 vcc, s78, v228
	s_and_saveexec_b64 s[78:79], vcc
	s_xor_b64 s[70:71], exec, s[78:79]
	v_add_u32_e32 v229, 0xfffff600, v230
	s_andn2_saveexec_b64 s[70:71], s[70:71]
	s_cbranch_execz .LBB0_140
	v_add_u32_e32 v229, 0xfffff800, v228
	v_and_b32_e32 v230, 0x80, v228
	v_mov_b32_e32 v231, 0xa00
	v_mov_b32_e32 v232, 0x800
	v_cmp_eq_u32_e32 vcc, 0, v230
	v_lshrrev_b32_e32 v229, 1, v229
	v_and_b32_e32 v229, 0x7fffff80, v229
	v_cndmask_b32_e32 v230, v231, v232, vcc
	v_add_u32_e32 v229, v230, v229
	s_movk_i32 s78, 0x60
	v_and_or_b32 v229, v228, s78, v229

.LBB0_141:
	s_andn2_saveexec_b64 s[68:69], s[68:69]
	s_cbranch_execz .LBB0_143
	v_add_u32_e32 v229, 0xfffffc00, v228
	v_and_b32_e32 v230, 0x80, v228
	v_mov_b32_e32 v231, 0xc00
	v_mov_b32_e32 v232, 0x600
	v_cmp_eq_u32_e32 vcc, 0, v230
	v_lshrrev_b32_e32 v229, 1, v229
	v_and_b32_e32 v229, 0x7fffff80, v229
	v_cndmask_b32_e32 v230, v231, v232, vcc
	v_add_u32_e32 v229, v230, v229
	s_movk_i32 s78, 0x60
	v_and_or_b32 v229, v228, s78, v229
.LBB0_143:
	s_or_b64 exec, exec, s[68:69]
.LBB0_144:
	s_andn2_saveexec_b64 s[82:83], s[82:83]
	v_lshlrev_b32_e32 v229, 3, v228
	v_ashrrev_i32_e32 v230, 1, v228
	v_and_b32_e32 v229, 0x400, v229
	v_and_b32_e32 v230, 0xffffff80, v230
	v_add_u32_e32 v229, v229, v230
	s_movk_i32 s78, 0x60
	v_and_or_b32 v229, v228, s78, v229
	s_or_b64 exec, exec, s[82:83]
	v_and_b32_e32 v228, 31, v228
	v_add_u32_e32 v228, v229, v228
	v_ashrrev_i32_e32 v229, 31, v228
	v_lshlrev_b32_e32 v245, 5, v218
	v_lshl_add_u64 v[228:229], v[228:229], 2, s[86:87]
	s_movk_i32 s78, 0x3800
	v_mad_i64_i32 v[230:231], s[86:87], v245, s78, v[228:229]
	v_or_b32_e32 v232, 1, v245
	v_or_b32_e32 v234, 2, v245
	v_or_b32_e32 v236, 3, v245
	v_or_b32_e32 v238, 4, v245
	v_or_b32_e32 v240, 5, v245
	v_or_b32_e32 v242, 6, v245
	v_or_b32_e32 v246, 7, v245
	v_mad_i64_i32 v[232:233], s[86:87], v232, s78, v[228:229]
	v_mad_i64_i32 v[234:235], s[86:87], v234, s78, v[228:229]
	v_mad_i64_i32 v[236:237], s[86:87], v236, s78, v[228:229]
	v_mad_i64_i32 v[238:239], s[86:87], v238, s78, v[228:229]
	v_mad_i64_i32 v[240:241], s[86:87], v240, s78, v[228:229]
	v_mad_i64_i32 v[242:243], s[86:87], v242, s78, v[228:229]
	v_mad_i64_i32 v[246:247], s[86:87], v246, s78, v[228:229]
	global_load_dword v153, v[230:231], off nt
	global_load_dword v157, v[232:233], off nt
	global_load_dword v158, v[234:235], off nt
	global_load_dword v159, v[236:237], off nt
	global_load_dword v156, v[238:239], off nt
	global_load_dword v160, v[240:241], off nt
	global_load_dword v154, v[242:243], off nt
	global_load_dword v155, v[246:247], off nt
	v_or_b32_e32 v230, 8, v245
	v_mad_i64_i32 v[230:231], s[86:87], v230, s78, v[228:229]
	v_or_b32_e32 v232, 9, v245
	v_or_b32_e32 v234, 10, v245
	v_or_b32_e32 v236, 11, v245
	v_or_b32_e32 v238, 12, v245
	v_or_b32_e32 v240, 13, v245
	v_or_b32_e32 v242, 14, v245
	v_or_b32_e32 v246, 15, v245
	v_mad_i64_i32 v[232:233], s[86:87], v232, s78, v[228:229]
	v_mad_i64_i32 v[234:235], s[86:87], v234, s78, v[228:229]
	v_mad_i64_i32 v[236:237], s[86:87], v236, s78, v[228:229]
	v_mad_i64_i32 v[238:239], s[86:87], v238, s78, v[228:229]
	v_mad_i64_i32 v[240:241], s[86:87], v240, s78, v[228:229]
	v_mad_i64_i32 v[242:243], s[86:87], v242, s78, v[228:229]
	v_mad_i64_i32 v[246:247], s[86:87], v246, s78, v[228:229]
	global_load_dword v162, v[230:231], off nt
	global_load_dword v165, v[232:233], off nt
	global_load_dword v166, v[234:235], off nt
	global_load_dword v167, v[236:237], off nt
	global_load_dword v164, v[238:239], off nt
	global_load_dword v168, v[240:241], off nt
	global_load_dword v161, v[242:243], off nt
	global_load_dword v163, v[246:247], off nt
	v_or_b32_e32 v230, 16, v245
	v_mad_i64_i32 v[230:231], s[86:87], v230, s78, v[228:229]
	v_or_b32_e32 v232, 17, v245
	v_or_b32_e32 v234, 18, v245
	v_or_b32_e32 v236, 19, v245
	v_or_b32_e32 v238, 20, v245
	v_or_b32_e32 v240, 21, v245
	v_or_b32_e32 v242, 22, v245
	v_or_b32_e32 v246, 23, v245
	v_mad_i64_i32 v[232:233], s[86:87], v232, s78, v[228:229]
	v_mad_i64_i32 v[234:235], s[86:87], v234, s78, v[228:229]
	v_mad_i64_i32 v[236:237], s[86:87], v236, s78, v[228:229]
	v_mad_i64_i32 v[238:239], s[86:87], v238, s78, v[228:229]
	v_mad_i64_i32 v[240:241], s[86:87], v240, s78, v[228:229]
	v_mad_i64_i32 v[242:243], s[86:87], v242, s78, v[228:229]
	v_mad_i64_i32 v[246:247], s[86:87], v246, s78, v[228:229]
	global_load_dword v170, v[230:231], off nt
	global_load_dword v173, v[232:233], off nt
	global_load_dword v174, v[234:235], off nt
	global_load_dword v175, v[236:237], off nt
	global_load_dword v172, v[238:239], off nt
	global_load_dword v176, v[240:241], off nt
	global_load_dword v169, v[242:243], off nt
	global_load_dword v171, v[246:247], off nt
	v_or_b32_e32 v230, 24, v245
	v_mad_i64_i32 v[230:231], s[86:87], v230, s78, v[228:229]
	v_or_b32_e32 v232, 25, v245
	v_or_b32_e32 v234, 26, v245
	v_or_b32_e32 v236, 27, v245
	v_or_b32_e32 v238, 28, v245
	v_or_b32_e32 v240, 29, v245
	v_or_b32_e32 v242, 30, v245
	v_or_b32_e32 v246, 31, v245
	v_mad_i64_i32 v[232:233], s[86:87], v232, s78, v[228:229]
	v_mad_i64_i32 v[234:235], s[86:87], v234, s78, v[228:229]
	v_mad_i64_i32 v[236:237], s[86:87], v236, s78, v[228:229]
	v_mad_i64_i32 v[238:239], s[86:87], v238, s78, v[228:229]
	v_mad_i64_i32 v[240:241], s[86:87], v240, s78, v[228:229]
	v_mad_i64_i32 v[242:243], s[86:87], v242, s78, v[228:229]
	v_mad_i64_i32 v[228:229], s[86:87], v246, s78, v[228:229]
	global_load_dword v177, v[230:231], off nt
	global_load_dword v179, v[232:233], off nt
	global_load_dword v180, v[234:235], off nt
	global_load_dword v181, v[236:237], off nt
	global_load_dword v178, v[238:239], off nt
	global_load_dword v184, v[240:241], off nt
	global_load_dword v182, v[242:243], off nt
	global_load_dword v183, v[228:229], off nt
.LBB0_147:
	s_or_b64 exec, exec, s[66:67]
	s_bitcmp0_b32 s2, 0
	s_cbranch_scc1 .Lbias_even
	s_waitcnt vmcnt(35)
	v_mul_f32_e32 v223, v109, v109
	v_mul_f32_e32 v225, v111, v111
	v_fmac_f32_e32 v223, v108, v108
	v_fmac_f32_e32 v225, v110, v110
	v_add_f32_e32 v223, v223, v225
	s_waitcnt vmcnt(34)
	v_mul_f32_e32 v225, v105, v105
	v_mul_f32_e32 v226, v107, v107
	v_fmac_f32_e32 v225, v104, v104
	v_fmac_f32_e32 v226, v106, v106
	v_add_f32_e32 v225, v225, v226
	v_add_f32_e32 v223, v223, v225
	s_waitcnt vmcnt(33)
	v_mul_f32_e32 v225, v101, v101
	v_mul_f32_e32 v226, v103, v103
	v_fmac_f32_e32 v225, v100, v100
	v_fmac_f32_e32 v226, v102, v102
	v_and_b32_e32 v219, 64, v244
	v_add_f32_e32 v225, v225, v226
	v_add_u32_e32 v224, 64, v219
	v_xor_b32_e32 v219, 1, v244
	v_add_f32_e32 v223, v223, v225
	s_waitcnt vmcnt(32)
	v_mul_f32_e32 v225, v97, v97
	v_mul_f32_e32 v226, v99, v99
	v_cmp_lt_i32_e32 vcc, v219, v224
	v_fmac_f32_e32 v225, v96, v96
	v_fmac_f32_e32 v226, v98, v98
	v_cndmask_b32_e32 v219, v244, v219, vcc
	v_add_f32_e32 v225, v225, v226
	v_lshlrev_b32_e32 v219, 2, v219
	v_add_f32_e32 v223, v223, v225
	ds_bpermute_b32 v225, v219, v223
	v_xor_b32_e32 v220, 2, v244
	v_cmp_lt_i32_e32 vcc, v220, v224
	v_xor_b32_e32 v221, 4, v244
	v_xor_b32_e32 v222, 8, v244
	v_cndmask_b32_e32 v220, v244, v220, vcc
	v_lshlrev_b32_e32 v220, 2, v220
	s_waitcnt lgkmcnt(0)
	v_add_f32_e32 v225, v223, v225
	ds_bpermute_b32 v227, v220, v225
	v_cmp_lt_i32_e32 vcc, v221, v224
	v_xor_b32_e32 v226, 16, v244
	s_mov_b32 s27, 0
	v_cndmask_b32_e32 v221, v244, v221, vcc
	v_lshlrev_b32_e32 v221, 2, v221
	s_waitcnt lgkmcnt(0)
	v_add_f32_e32 v225, v225, v227
	ds_bpermute_b32 v227, v221, v225
	v_cmp_lt_i32_e32 vcc, v222, v224
	s_lshr_b32 s26, s65, 8
	s_lshl_b64 s[26:27], s[26:27], 23
	v_cndmask_b32_e32 v222, v244, v222, vcc
	v_cmp_lt_i32_e32 vcc, v226, v224
	v_lshlrev_b32_e32 v222, 2, v222
	s_waitcnt lgkmcnt(0)
	v_add_f32_e32 v225, v225, v227
	v_cndmask_b32_e32 v223, v244, v226, vcc
	v_xor_b32_e32 v226, 32, v244
	v_cmp_lt_i32_e32 vcc, v226, v224
	v_lshlrev_b32_e32 v223, 2, v223
	s_add_u32 s26, s58, s26
	v_cndmask_b32_e32 v224, v244, v226, vcc
	ds_bpermute_b32 v226, v222, v225
	v_lshlrev_b32_e32 v224, 2, v224
	s_addc_u32 s27, s59, s27
	s_add_u32 s60, s26, 0x400000
	s_addc_u32 s61, s27, 0
	s_waitcnt lgkmcnt(0)
	v_add_f32_e32 v225, v225, v226
	ds_bpermute_b32 v226, v223, v225
	s_ashr_i32 s57, s56, 31
	s_lshl_b64 s[50:51], s[56:57], 22
	s_add_u32 s26, s58, s50
	s_addc_u32 s27, s59, s51
	s_waitcnt lgkmcnt(0)
	v_add_f32_e32 v225, v225, v226
	ds_bpermute_b32 v226, v224, v225
	s_and_b64 vcc, exec, s[54:55]
	s_cbranch_vccz .LBB0_162
	s_lshl_b32 s54, s3, 14
	s_and_b32 s54, s54, 0x7c000
	s_add_u32 s54, s60, s54
	s_addc_u32 s55, s61, 0
	s_cbranch_execz .LBB0_163
	s_branch .LBB0_164

.LBB0_164:
	s_waitcnt vmcnt(6)
	v_pk_add_f32 v[128:129], v[128:129], 1.0 op_sel_hi:[1,0]
	s_mov_b32 s43, 0x800000
	s_waitcnt vmcnt(5)
	v_pk_mul_f32 v[120:121], v[120:121], v[128:129]
	s_waitcnt lgkmcnt(0)
	v_add_f32_e32 v128, v225, v226
	v_mov_b32_e32 v129, 0x358637bd
	v_fmac_f32_e32 v129, 0x3a800000, v128
	v_mul_f32_e32 v128, 0x4b800000, v129
	v_cmp_gt_f32_e32 vcc, s43, v129
	s_waitcnt vmcnt(2)
	v_pk_add_f32 v[116:117], v[116:117], 1.0 op_sel_hi:[1,0]
	v_pk_add_f32 v[142:143], v[142:143], 1.0 op_sel_hi:[1,0]
	v_cndmask_b32_e32 v128, v129, v128, vcc
	v_rsq_f32_e32 v128, v128
	v_pk_mul_f32 v[112:113], v[112:113], v[116:117]
	v_pk_add_f32 v[140:141], v[140:141], 1.0 op_sel_hi:[1,0]
	v_pk_mul_f32 v[134:135], v[134:135], v[142:143]
	v_mul_f32_e32 v116, 0x45800000, v128
	v_cndmask_b32_e32 v116, v128, v116, vcc
	v_pk_mul_f32 v[132:133], v[132:133], v[140:141]
	v_pk_mul_f32 v[108:109], v[108:109], v[116:117] op_sel_hi:[1,0]
	v_pk_mul_f32 v[110:111], v[110:111], v[116:117] op_sel_hi:[1,0]
	v_pk_add_f32 v[118:119], v[118:119], 1.0 op_sel_hi:[1,0]
	v_pk_fma_f32 v[110:111], v[134:135], v[110:111], v[82:83]
	v_pk_fma_f32 v[108:109], v[132:133], v[108:109], v[80:81]
	v_pk_mul_f32 v[114:115], v[114:115], v[118:119]
	v_lshl_add_u64 v[118:119], v[144:145], 3, s[54:55]
	v_cvt_pk_bf16_f32 v108, v108, v109
	v_cvt_pk_bf16_f32 v109, v110, v111
	global_store_dwordx2 v[118:119], v[108:109], off
	v_mul_f32_e32 v108, v93, v93
	v_mul_f32_e32 v109, v95, v95
	v_fmac_f32_e32 v108, v92, v92
	v_fmac_f32_e32 v109, v94, v94
	v_add_f32_e32 v108, v108, v109
	v_mul_f32_e32 v109, v89, v89
	v_mul_f32_e32 v110, v91, v91
	v_fmac_f32_e32 v109, v88, v88
	v_fmac_f32_e32 v110, v90, v90
	v_add_f32_e32 v109, v109, v110
	v_add_f32_e32 v108, v108, v109
	v_mul_f32_e32 v109, v85, v85
	v_mul_f32_e32 v110, v87, v87
	v_fmac_f32_e32 v109, v84, v84
	v_fmac_f32_e32 v110, v86, v86
	v_add_f32_e32 v109, v109, v110
	v_add_f32_e32 v108, v108, v109
	v_mul_f32_e32 v109, v77, v77
	v_mul_f32_e32 v110, v79, v79
	v_fmac_f32_e32 v109, v76, v76
	v_fmac_f32_e32 v110, v78, v78
	v_add_f32_e32 v109, v109, v110
	v_add_f32_e32 v108, v108, v109
	ds_bpermute_b32 v109, v219, v108
	v_pk_add_f32 v[138:139], v[138:139], 1.0 op_sel_hi:[1,0]
	v_pk_add_f32 v[136:137], v[136:137], 1.0 op_sel_hi:[1,0]
	v_pk_mul_f32 v[126:127], v[126:127], v[138:139]
	v_pk_mul_f32 v[124:125], v[124:125], v[136:137]
	s_waitcnt lgkmcnt(0)
	v_add_f32_e32 v108, v108, v109
	ds_bpermute_b32 v109, v220, v108
	v_pk_mul_f32 v[104:105], v[104:105], v[116:117] op_sel_hi:[1,0]
	v_pk_mul_f32 v[106:107], v[106:107], v[116:117] op_sel_hi:[1,0]
	v_pk_fma_f32 v[104:105], v[124:125], v[104:105], v[72:73]
	v_pk_fma_f32 v[106:107], v[126:127], v[106:107], v[74:75]
	v_cvt_pk_bf16_f32 v104, v104, v105
	v_cvt_pk_bf16_f32 v105, v106, v107
	global_store_dwordx2 v[118:119], v[104:105], off offset:512
	s_waitcnt lgkmcnt(0)
	v_add_f32_e32 v104, v108, v109
	ds_bpermute_b32 v105, v221, v104
	v_pk_add_f32 v[130:131], v[130:131], 1.0 op_sel_hi:[1,0]
	v_pk_mul_f32 v[100:101], v[100:101], v[116:117] op_sel_hi:[1,0]
	v_pk_mul_f32 v[122:123], v[122:123], v[130:131]
	v_pk_mul_f32 v[102:103], v[102:103], v[116:117] op_sel_hi:[1,0]
	s_waitcnt lgkmcnt(0)
	v_add_f32_e32 v104, v104, v105
	ds_bpermute_b32 v105, v222, v104
	s_waitcnt vmcnt(3)
	v_pk_fma_f32 v[102:103], v[122:123], v[102:103], v[66:67]
	v_pk_fma_f32 v[100:101], v[120:121], v[100:101], v[64:65]
	v_pk_mul_f32 v[96:97], v[96:97], v[116:117] op_sel_hi:[1,0]
	v_cvt_pk_bf16_f32 v100, v100, v101
	v_cvt_pk_bf16_f32 v101, v102, v103
	s_waitcnt lgkmcnt(0)
	v_add_f32_e32 v102, v104, v105
	ds_bpermute_b32 v103, v223, v102
	s_waitcnt vmcnt(2)
	s_branch .Lbias_join
.Lbias_even:
	s_waitcnt vmcnt(63)
	v_mul_f32_e32 v223, v109, v109
	v_mul_f32_e32 v225, v111, v111
	v_fmac_f32_e32 v223, v108, v108
	v_fmac_f32_e32 v225, v110, v110
	v_add_f32_e32 v223, v223, v225
	s_waitcnt vmcnt(63)
	v_mul_f32_e32 v225, v105, v105
	v_mul_f32_e32 v226, v107, v107
	v_fmac_f32_e32 v225, v104, v104
	v_fmac_f32_e32 v226, v106, v106
	v_add_f32_e32 v225, v225, v226
	v_add_f32_e32 v223, v223, v225
	s_waitcnt vmcnt(63)
	v_mul_f32_e32 v225, v101, v101
	v_mul_f32_e32 v226, v103, v103
	v_fmac_f32_e32 v225, v100, v100
	v_fmac_f32_e32 v226, v102, v102
	v_and_b32_e32 v219, 64, v244
	v_add_f32_e32 v225, v225, v226
	v_add_u32_e32 v224, 64, v219
	v_xor_b32_e32 v219, 1, v244
	v_add_f32_e32 v223, v223, v225
	s_waitcnt vmcnt(63)
	v_mul_f32_e32 v225, v97, v97
	v_mul_f32_e32 v226, v99, v99
	v_cmp_lt_i32_e32 vcc, v219, v224
	v_fmac_f32_e32 v225, v96, v96
	v_fmac_f32_e32 v226, v98, v98
	v_cndmask_b32_e32 v219, v244, v219, vcc
	v_add_f32_e32 v225, v225, v226
	v_lshlrev_b32_e32 v219, 2, v219
	v_add_f32_e32 v223, v223, v225
	ds_bpermute_b32 v225, v219, v223
	v_xor_b32_e32 v220, 2, v244
	v_cmp_lt_i32_e32 vcc, v220, v224
	v_xor_b32_e32 v221, 4, v244
	v_xor_b32_e32 v222, 8, v244
	v_cndmask_b32_e32 v220, v244, v220, vcc
	v_lshlrev_b32_e32 v220, 2, v220
	s_waitcnt lgkmcnt(0)
	v_add_f32_e32 v225, v223, v225
	ds_bpermute_b32 v227, v220, v225
	v_cmp_lt_i32_e32 vcc, v221, v224
	v_xor_b32_e32 v226, 16, v244
	s_mov_b32 s27, 0
	v_cndmask_b32_e32 v221, v244, v221, vcc
	v_lshlrev_b32_e32 v221, 2, v221
	s_waitcnt lgkmcnt(0)
	v_add_f32_e32 v225, v225, v227
	ds_bpermute_b32 v227, v221, v225
	v_cmp_lt_i32_e32 vcc, v222, v224
	s_lshr_b32 s26, s65, 8
	s_lshl_b64 s[26:27], s[26:27], 23
	v_cndmask_b32_e32 v222, v244, v222, vcc
	v_cmp_lt_i32_e32 vcc, v226, v224
	v_lshlrev_b32_e32 v222, 2, v222
	s_waitcnt lgkmcnt(0)
	v_add_f32_e32 v225, v225, v227
	v_cndmask_b32_e32 v223, v244, v226, vcc
	v_xor_b32_e32 v226, 32, v244
	v_cmp_lt_i32_e32 vcc, v226, v224
	v_lshlrev_b32_e32 v223, 2, v223
	s_add_u32 s26, s58, s26
	v_cndmask_b32_e32 v224, v244, v226, vcc
	ds_bpermute_b32 v226, v222, v225
	v_lshlrev_b32_e32 v224, 2, v224
	s_addc_u32 s27, s59, s27
	s_add_u32 s60, s26, 0x400000
	s_addc_u32 s61, s27, 0
	s_waitcnt lgkmcnt(0)
	v_add_f32_e32 v225, v225, v226
	ds_bpermute_b32 v226, v223, v225
	s_ashr_i32 s57, s56, 31
	s_lshl_b64 s[50:51], s[56:57], 22
	s_add_u32 s26, s58, s50
	s_addc_u32 s27, s59, s51
	s_waitcnt lgkmcnt(0)
	v_add_f32_e32 v225, v225, v226
	ds_bpermute_b32 v226, v224, v225
	s_and_b64 vcc, exec, s[54:55]
	s_cbranch_vccz .Lbe_162
	s_lshl_b32 s54, s3, 14
	s_and_b32 s54, s54, 0x7c000
	s_add_u32 s54, s60, s54
	s_addc_u32 s55, s61, 0
	s_cbranch_execz .Lbe_163
	s_branch .Lbe_164

.Lbe_164:
	s_waitcnt vmcnt(63)
	v_pk_add_f32 v[128:129], v[128:129], 1.0 op_sel_hi:[1,0]
	s_mov_b32 s43, 0x800000
	s_waitcnt vmcnt(63)
	v_pk_mul_f32 v[120:121], v[120:121], v[128:129]
	s_waitcnt lgkmcnt(0)
	v_add_f32_e32 v128, v225, v226
	v_mov_b32_e32 v129, 0x358637bd
	v_fmac_f32_e32 v129, 0x3a800000, v128
	v_mul_f32_e32 v128, 0x4b800000, v129
	v_cmp_gt_f32_e32 vcc, s43, v129
	s_waitcnt vmcnt(63)
	v_pk_add_f32 v[116:117], v[116:117], 1.0 op_sel_hi:[1,0]
	v_pk_add_f32 v[142:143], v[142:143], 1.0 op_sel_hi:[1,0]
	v_cndmask_b32_e32 v128, v129, v128, vcc
	v_rsq_f32_e32 v128, v128
	v_pk_mul_f32 v[112:113], v[112:113], v[116:117]
	v_pk_add_f32 v[140:141], v[140:141], 1.0 op_sel_hi:[1,0]
	v_pk_mul_f32 v[134:135], v[134:135], v[142:143]
	v_mul_f32_e32 v116, 0x45800000, v128
	v_cndmask_b32_e32 v116, v128, v116, vcc
	v_pk_mul_f32 v[132:133], v[132:133], v[140:141]
	v_pk_mul_f32 v[108:109], v[108:109], v[116:117] op_sel_hi:[1,0]
	v_pk_mul_f32 v[110:111], v[110:111], v[116:117] op_sel_hi:[1,0]
	v_pk_add_f32 v[118:119], v[118:119], 1.0 op_sel_hi:[1,0]
	v_pk_fma_f32 v[110:111], v[134:135], v[110:111], v[82:83]
	v_pk_fma_f32 v[108:109], v[132:133], v[108:109], v[80:81]
	v_pk_mul_f32 v[114:115], v[114:115], v[118:119]
	v_lshl_add_u64 v[118:119], v[144:145], 3, s[54:55]
	v_cvt_pk_bf16_f32 v108, v108, v109
	v_cvt_pk_bf16_f32 v109, v110, v111
	global_store_dwordx2 v[118:119], v[108:109], off
	v_mul_f32_e32 v108, v93, v93
	v_mul_f32_e32 v109, v95, v95
	v_fmac_f32_e32 v108, v92, v92
	v_fmac_f32_e32 v109, v94, v94
	v_add_f32_e32 v108, v108, v109
	v_mul_f32_e32 v109, v89, v89
	v_mul_f32_e32 v110, v91, v91
	v_fmac_f32_e32 v109, v88, v88
	v_fmac_f32_e32 v110, v90, v90
	v_add_f32_e32 v109, v109, v110
	v_add_f32_e32 v108, v108, v109
	v_mul_f32_e32 v109, v85, v85
	v_mul_f32_e32 v110, v87, v87
	v_fmac_f32_e32 v109, v84, v84
	v_fmac_f32_e32 v110, v86, v86
	v_add_f32_e32 v109, v109, v110
	v_add_f32_e32 v108, v108, v109
	v_mul_f32_e32 v109, v77, v77
	v_mul_f32_e32 v110, v79, v79
	v_fmac_f32_e32 v109, v76, v76
	v_fmac_f32_e32 v110, v78, v78
	v_add_f32_e32 v109, v109, v110
	v_add_f32_e32 v108, v108, v109
	ds_bpermute_b32 v109, v219, v108
	v_pk_add_f32 v[138:139], v[138:139], 1.0 op_sel_hi:[1,0]
	v_pk_add_f32 v[136:137], v[136:137], 1.0 op_sel_hi:[1,0]
	v_pk_mul_f32 v[126:127], v[126:127], v[138:139]
	v_pk_mul_f32 v[124:125], v[124:125], v[136:137]
	s_waitcnt lgkmcnt(0)
	v_add_f32_e32 v108, v108, v109
	ds_bpermute_b32 v109, v220, v108
	v_pk_mul_f32 v[104:105], v[104:105], v[116:117] op_sel_hi:[1,0]
	v_pk_mul_f32 v[106:107], v[106:107], v[116:117] op_sel_hi:[1,0]
	v_pk_fma_f32 v[104:105], v[124:125], v[104:105], v[72:73]
	v_pk_fma_f32 v[106:107], v[126:127], v[106:107], v[74:75]
	v_cvt_pk_bf16_f32 v104, v104, v105
	v_cvt_pk_bf16_f32 v105, v106, v107
	global_store_dwordx2 v[118:119], v[104:105], off offset:512
	s_waitcnt lgkmcnt(0)
	v_add_f32_e32 v104, v108, v109
	ds_bpermute_b32 v105, v221, v104
	v_pk_add_f32 v[130:131], v[130:131], 1.0 op_sel_hi:[1,0]
	v_pk_mul_f32 v[100:101], v[100:101], v[116:117] op_sel_hi:[1,0]
	v_pk_mul_f32 v[122:123], v[122:123], v[130:131]
	v_pk_mul_f32 v[102:103], v[102:103], v[116:117] op_sel_hi:[1,0]
	s_waitcnt lgkmcnt(0)
	v_add_f32_e32 v104, v104, v105
	ds_bpermute_b32 v105, v222, v104
	s_waitcnt vmcnt(63)
	v_pk_fma_f32 v[102:103], v[122:123], v[102:103], v[66:67]
	v_pk_fma_f32 v[100:101], v[120:121], v[100:101], v[64:65]
	v_pk_mul_f32 v[96:97], v[96:97], v[116:117] op_sel_hi:[1,0]
	v_cvt_pk_bf16_f32 v100, v100, v101
	v_cvt_pk_bf16_f32 v101, v102, v103
	s_waitcnt lgkmcnt(0)
	v_add_f32_e32 v102, v104, v105
	ds_bpermute_b32 v103, v223, v102
	s_waitcnt vmcnt(63)
.Lbias_join:
	v_pk_fma_f32 v[96:97], v[112:113], v[96:97], v[56:57]
	global_store_dwordx2 v[118:119], v[100:101], off offset:1024
	v_cvt_pk_bf16_f32 v100, v96, v97
	v_pk_mul_f32 v[98:99], v[98:99], v[116:117] op_sel_hi:[1,0]
	s_waitcnt lgkmcnt(0)
	v_add_f32_e32 v96, v102, v103
	ds_bpermute_b32 v97, v224, v96
	v_pk_fma_f32 v[98:99], v[114:115], v[98:99], v[58:59]
	s_andn2_b64 vcc, exec, s[52:53]
	v_cvt_pk_bf16_f32 v101, v98, v99
	global_store_dwordx2 v[118:119], v[100:101], off offset:1536
	s_cbranch_vccnz .LBB0_166
	s_lshl_b32 s43, s48, 11
	s_and_b32 s43, s43, 0x7c800
	s_add_u32 s52, s60, s43
	s_addc_u32 s53, s61, 0
	s_cbranch_execz .LBB0_167
	s_branch .LBB0_168
